# P0 x f32 streaming loads marked nt (read-once data)
# speedup vs baseline: 1.0210x; 1.0205x over previous
; DI unsigned cvt_pk(float lo, float hi) { const f32x2 v = {lo, hi}; return __builtin_bit_cast(unsigned, __builtin_convertvector(v, bf16v2)); }
; DI void p0_prologue(const Params& P, LAS unsigned char* lds) {
;     ...
;         for (int row0 = bid * 8 + wid; row0 < NTOK; row0 += 2 * G * 8) {
;             const int row1 = row0 + G * 8; const bool has1 = row1 < NTOK;
;             const f32x4* xr0 = (const f32x4*)(P.x + (size_t)row0 * DM);
;             const f32x4* xr1 = (const f32x4*)(P.x + (size_t)(has1 ? row1 : row0) * DM);
;             f32x4 v0[4], v1[4];
; #pragma unroll
;             for (int i = 0; i < 4; ++i) { v0[i] = xr0[lane + 64 * i]; v1[i] = xr1[lane + 64 * i]; }
;             float s0 = 0.f, s1 = 0.f;
; #pragma unroll
;             for (int i = 0; i < 4; ++i) {
;                 s0 += v0[i][0] * v0[i][0] + v0[i][1] * v0[i][1] + v0[i][2] * v0[i][2] + v0[i][3] * v0[i][3];
;                 s1 += v1[i][0] * v1[i][0] + v1[i][1] * v1[i][1] + v1[i][2] * v1[i][2] + v1[i][3] * v1[i][3];
;                 u32x2 w; w.x = cvt_pk(v0[i][0], v0[i][1]); w.y = cvt_pk(v0[i][2], v0[i][3]);
;                 *(u32x2*)(xb + (size_t)row0 * DM + 4 * (lane + 64 * i)) = w;
;                 if (has1) { u32x2 w1; w1.x = cvt_pk(v1[i][0], v1[i][1]); w1.y = cvt_pk(v1[i][2], v1[i][3]); *(u32x2*)(xb + (size_t)row1 * DM + 4 * (lane + 64 * i)) = w1; }
.LBB0_8:
	v_add_u32_e32 v42, s70, v44
	v_cmp_gt_i32_e64 s[0:1], s2, v42
	v_ashrrev_i32_e32 v45, 31, v44
	s_waitcnt lgkmcnt(0)
	v_lshlrev_b64 v[4:5], 12, v[44:45]
	v_cndmask_b32_e64 v2, v44, v42, s[0:1]
	v_ashrrev_i32_e32 v3, 31, v2
	v_lshlrev_b64 v[2:3], 12, v[2:3]
	v_lshl_add_u64 v[4:5], v[38:39], 0, v[4:5]
	v_lshl_add_u64 v[2:3], v[38:39], 0, v[2:3]
	global_load_dwordx4 v[30:33], v[4:5], off nt
	global_load_dwordx4 v[22:25], v[4:5], off offset:1024 nt
	global_load_dwordx4 v[26:29], v[2:3], off nt
	global_load_dwordx4 v[18:21], v[2:3], off offset:1024 nt
	global_load_dwordx4 v[14:17], v[4:5], off offset:2048 nt
	global_load_dwordx4 v[6:9], v[4:5], off offset:3072 nt
	global_load_dwordx4 v[10:13], v[2:3], off offset:2048 nt
	s_nop 0
	global_load_dwordx4 v[2:5], v[2:3], off offset:3072 nt
	v_ashrrev_i32_e32 v43, 31, v42
	v_lshlrev_b64 v[46:47], 11, v[44:45]
	v_lshlrev_b64 v[56:57], 11, v[42:43]
	v_lshl_add_u64 v[48:49], v[40:41], 0, v[46:47]
	v_lshl_add_u64 v[46:47], s[26:27], 0, v[56:57]
	v_lshlrev_b32_e32 v34, 1, v36
	s_waitcnt vmcnt(7)
	v_cvt_pk_bf16_f32 v56, v30, v31
	v_cvt_pk_bf16_f32 v57, v32, v33
	global_store_dwordx2 v[48:49], v[56:57], off
	s_and_saveexec_b64 s[4:5], s[0:1]
	s_cbranch_execz .LBB0_10
	s_waitcnt vmcnt(6)
	v_cvt_pk_bf16_f32 v56, v26, v27
	v_cvt_pk_bf16_f32 v57, v28, v29
	v_lshl_add_u64 v[58:59], v[46:47], 0, v[34:35]
	global_store_dwordx2 v[58:59], v[56:57], off
